# phase-1/5 bf16 result stores made write-through (sc1) so the grid-barrier L2 writeback has less dirty data
# baseline (speedup 1.0000x reference)
.LBB0_135:
	v_lshlrev_b32_e32 v2, 4, v1
	v_ashrrev_i32_e32 v4, 3, v11
	v_and_b32_e32 v2, 0x70, v2
	v_mov_b32_e32 v3, v0
	v_lshl_add_u64 v[6:7], s[2:3], 0, v[2:3]
	v_lshrrev_b32_e32 v3, 2, v4
	v_xor_b32_e32 v3, v3, v1
	v_add_u32_e32 v12, s52, v4
	v_lshlrev_b32_e32 v3, 4, v3
	v_lshlrev_b32_e32 v2, 7, v12
	v_and_b32_e32 v3, 0x70, v3
	s_waitcnt lgkmcnt(0)
	s_barrier
	v_add3_u32 v2, s53, v2, v3
	ds_read_b128 v[150:153], v2
	v_mul_lo_u32 v8, s4, v12
	v_mov_b32_e32 v9, v0
	v_lshl_add_u64 v[166:167], v[8:9], 1, v[6:7]
	s_lshl_b32 s0, s4, 3
	v_add_u32_e32 v8, s0, v8
	v_lshl_add_u64 v[168:169], v[8:9], 1, v[6:7]
	v_add_u32_e32 v2, 8, v12
	v_lshlrev_b32_e32 v3, 7, v2
	v_lshrrev_b32_e32 v2, 2, v2
	v_xor_b32_e32 v2, v2, v1
	v_lshlrev_b32_e32 v2, 4, v2
	v_and_b32_e32 v2, 0x70, v2
	v_add3_u32 v2, s53, v3, v2
	ds_read_b128 v[154:157], v2
	v_add_u32_e32 v8, s0, v8
	s_nop 1
	v_add_u32_e32 v2, 16, v12
	v_lshlrev_b32_e32 v3, 7, v2
	v_lshrrev_b32_e32 v2, 2, v2
	v_xor_b32_e32 v2, v2, v1
	v_lshlrev_b32_e32 v2, 4, v2
	v_and_b32_e32 v2, 0x70, v2
	v_add3_u32 v2, s53, v3, v2
	ds_read_b128 v[158:161], v2
	v_lshl_add_u64 v[170:171], v[8:9], 1, v[6:7]
	v_add_u32_e32 v8, s0, v8
	v_lshl_add_u64 v[172:173], v[8:9], 1, v[6:7]
	s_nop 1
	v_add_u32_e32 v2, 24, v12
	v_lshlrev_b32_e32 v3, 7, v2
	v_lshrrev_b32_e32 v2, 2, v2
	v_xor_b32_e32 v1, v2, v1
	v_lshlrev_b32_e32 v1, 4, v1
	v_and_b32_e32 v1, 0x70, v1
	v_add3_u32 v1, s53, v3, v1
	ds_read_b128 v[162:165], v1
	s_waitcnt lgkmcnt(3)
	global_store_dwordx4 v[166:167], v[150:153], off sc1
	s_waitcnt lgkmcnt(2)
	global_store_dwordx4 v[168:169], v[154:157], off sc1
	s_waitcnt lgkmcnt(1)
	global_store_dwordx4 v[170:171], v[158:161], off sc1
	s_waitcnt lgkmcnt(0)
	global_store_dwordx4 v[172:173], v[162:165], off sc1
	s_waitcnt lgkmcnt(0)
	s_barrier

.LBB0_221:
	s_lshl_b32 s52, s45, 5
	s_cmp_eq_u32 s68, 10
	s_cselect_b64 s[88:89], -1, 0
	s_cmp_lg_u32 s68, 10
	s_cselect_b64 s[60:61], -1, 0
	s_and_b64 s[0:1], s[10:11], exec
	s_mov_b32 s0, 0xb080000
	s_cselect_b32 s19, s0, 0xa600000
	s_cmp_gt_i32 s45, 1
	s_cselect_b64 s[66:67], -1, 0
	s_cmp_eq_u32 s45, 2
	s_cselect_b64 s[20:21], -1, 0
	s_lshl_b32 s2, s17, 7
	s_add_i32 s3, s2, 0xffc00000
	s_and_b64 s[0:1], s[10:11], exec
	v_mov_b32_e32 v143, v249
	v_mov_b32_e32 v142, v1
	s_mov_b32 s0, 0x2c00000
	v_cndmask_b32_e64 v131, 0, 1, s[12:13]
	v_lshlrev_b32_e32 v130, 2, v143
	s_cselect_b32 s24, s3, s2
	s_cselect_b32 s55, s0, 0x2180000
	v_add_u32_e32 v132, s52, v130
	s_mov_b64 s[2:3], -1
	s_and_b64 vcc, exec, s[60:61]
	v_cmp_ne_u32_e64 s[0:1], 1, v131
	s_cbranch_vccz .LBB0_248
	s_and_b64 vcc, exec, s[0:1]
	s_cbranch_vccnz .LBB0_247
	s_lshl_b32 s4, s17, 6
	v_readlane_b32 s76, v251, 3
	s_add_i32 s5, s4, 0xffe00000
	v_readlane_b32 s77, v251, 4
	v_readlane_b32 s78, v251, 5
	v_readlane_b32 s79, v251, 6
	v_readlane_b32 s80, v251, 7
	v_readlane_b32 s81, v251, 8
	s_and_b64 s[2:3], s[10:11], exec
	v_readlane_b32 s82, v251, 9
	v_readlane_b32 s83, v251, 10
	s_mov_b64 s[76:77], s[80:81]
	s_cselect_b32 s2, s5, s4
	s_lshl_b32 s4, s17, 3
	s_mov_b64 s[78:79], s[82:83]
	s_mov_b32 s3, s25
	s_add_u32 s12, s78, s19
	s_addc_u32 s13, s79, 0
	s_lshl_b64 s[2:3], s[2:3], 2
	s_mov_b32 s5, s25
	s_add_u32 s2, s12, s2
	s_addc_u32 s3, s13, s3
	s_lshl_b64 s[4:5], s[4:5], 2
	v_readlane_b32 s12, v252, 47
	v_readlane_b32 s13, v252, 48
	s_add_u32 s4, s12, s4
	s_addc_u32 s5, s13, s5
	v_cmp_gt_i32_e32 vcc, 2, v143
	v_ashrrev_i32_e32 v131, 31, v130
	s_and_b64 s[12:13], s[20:21], vcc
	v_lshlrev_b32_e32 v134, 3, v142
	v_lshl_add_u64 v[136:137], v[130:131], 2, s[4:5]
	s_mov_b64 s[50:51], -1
	s_and_b64 vcc, exec, s[66:67]
	s_cbranch_vccz .LBB0_227
	s_and_saveexec_b64 s[50:51], s[12:13]
	s_cbranch_execz .LBB0_226
	s_mov_b32 s4, 0x3d3504f3
	v_mov_b32_e32 v135, v0
	v_pk_mul_f32 v[140:141], v[100:101], s[4:5] op_sel_hi:[1,0]
	v_pk_mul_f32 v[138:139], v[98:99], s[4:5] op_sel_hi:[1,0]
	v_lshl_add_u64 v[144:145], v[134:135], 2, v[136:137]
	global_store_dwordx4 v[144:145], v[138:141], off sc1

.LBB0_229:
	v_cndmask_b32_e64 v131, 0, 1, s[66:67]
	v_cmp_ne_u32_e64 s[2:3], 1, v131
	s_andn2_b64 vcc, exec, s[66:67]
	s_mov_b64 s[50:51], -1
	s_cbranch_vccnz .LBB0_241
	s_and_saveexec_b64 s[50:51], s[12:13]
	s_cbranch_execz .LBB0_232
	s_mov_b32 s4, 0x3d3504f3
	v_add_u32_e32 v148, 0x80, v134
	v_mov_b32_e32 v149, v0
	v_pk_mul_f32 v[146:147], v[104:105], s[4:5] op_sel_hi:[1,0]
	v_pk_mul_f32 v[144:145], v[102:103], s[4:5] op_sel_hi:[1,0]
	v_lshl_add_u64 v[148:149], v[148:149], 2, v[136:137]
	global_store_dwordx4 v[148:149], v[144:147], off sc1

.LBB0_234:
	s_and_saveexec_b64 s[50:51], s[12:13]
	s_cbranch_execz .LBB0_236
	s_mov_b32 s4, 0x3d3504f3
	v_add_u32_e32 v148, 0x100, v134
	v_mov_b32_e32 v149, v0
	v_pk_mul_f32 v[146:147], v[108:109], s[4:5] op_sel_hi:[1,0]
	v_pk_mul_f32 v[144:145], v[106:107], s[4:5] op_sel_hi:[1,0]
	v_lshl_add_u64 v[148:149], v[148:149], 2, v[136:137]
	global_store_dwordx4 v[148:149], v[144:147], off sc1

.LBB0_238:
	s_and_saveexec_b64 s[2:3], s[12:13]
	s_cbranch_execz .LBB0_240
	s_mov_b32 s4, 0x3d3504f3
	v_add_u32_e32 v134, 0x180, v134
	v_mov_b32_e32 v135, v0
	v_pk_mul_f32 v[146:147], v[120:121], s[4:5] op_sel_hi:[1,0]
	v_pk_mul_f32 v[144:145], v[118:119], s[4:5] op_sel_hi:[1,0]
	v_lshl_add_u64 v[134:135], v[134:135], 2, v[136:137]
	global_store_dwordx4 v[134:135], v[144:147], off sc1

.LBB0_286:
	s_waitcnt lgkmcnt(0)
	s_barrier
	v_and_b32_e32 v131, 15, v142
	v_readlane_b32 s12, v251, 51
	v_cmp_gt_u32_e32 vcc, 8, v131
	v_readlane_b32 s13, v251, 52
	s_or_b64 s[80:81], s[12:13], vcc
	s_and_saveexec_b64 s[12:13], s[80:81]
	s_cbranch_execz .LBB0_288
	v_lshrrev_b32_e32 v131, 3, v131
	v_mul_u32_u24_e32 v131, s76, v131
	v_and_b32_e32 v135, s69, v142
	v_lshlrev_b32_e32 v131, 1, v131
	v_lshl_or_b32 v136, v135, 4, v131
	v_ashrrev_i32_e32 v131, 4, v133
	v_add_u32_e32 v135, s75, v131
	v_xor_b32_e32 v131, v131, v142
	v_mov_b32_e32 v137, v0
	v_lshlrev_b32_e32 v131, 4, v131
	v_lshl_add_u64 v[140:141], s[2:3], 0, v[136:137]
	v_lshlrev_b32_e32 v136, 8, v135
	v_and_b32_e32 v131, 0xf0, v131
	v_add3_u32 v131, s53, v131, v136
	ds_read_b128 v[150:153], v131
	v_mul_lo_u32 v144, s65, v135
	v_mov_b32_e32 v145, v0
	v_lshl_add_u64 v[166:167], v[144:145], 1, v[140:141]
	v_add_u32_e32 v131, 4, v135
	s_lshl_b32 s2, s65, 2
	v_add_u32_e32 v144, s2, v144
	v_lshlrev_b32_e32 v136, 8, v131
	v_xor_b32_e32 v131, v131, v142
	v_lshlrev_b32_e32 v131, 4, v131
	v_and_b32_e32 v131, 0xf0, v131
	v_add3_u32 v131, s53, v131, v136
	ds_read_b128 v[154:157], v131
	v_lshl_add_u64 v[168:169], v[144:145], 1, v[140:141]
	v_add_u32_e32 v131, 8, v135
	v_add_u32_e32 v144, s2, v144
	v_lshl_add_u64 v[170:171], v[144:145], 1, v[140:141]
	s_nop 0
	v_lshlrev_b32_e32 v136, 8, v131
	v_xor_b32_e32 v131, v131, v142
	v_lshlrev_b32_e32 v131, 4, v131
	v_and_b32_e32 v131, 0xf0, v131
	v_add3_u32 v131, s53, v131, v136
	ds_read_b128 v[158:161], v131
	v_add_u32_e32 v131, 12, v135
	v_lshlrev_b32_e32 v135, 8, v131
	v_xor_b32_e32 v131, v131, v142
	v_lshlrev_b32_e32 v131, 4, v131
	v_and_b32_e32 v131, 0xf0, v131
	v_add3_u32 v131, s53, v131, v135
	s_nop 0
	v_add_u32_e32 v136, s2, v144
	v_mov_b32_e32 v137, v0
	v_lshl_add_u64 v[172:173], v[136:137], 1, v[140:141]
	ds_read_b128 v[162:165], v131
	s_waitcnt lgkmcnt(3)
	global_store_dwordx4 v[166:167], v[150:153], off sc1
	s_waitcnt lgkmcnt(2)
	global_store_dwordx4 v[168:169], v[154:157], off sc1
	s_waitcnt lgkmcnt(1)
	global_store_dwordx4 v[170:171], v[158:161], off sc1
	s_waitcnt lgkmcnt(0)
	global_store_dwordx4 v[172:173], v[162:165], off sc1

.LBB0_302:
	v_lshlrev_b32_e32 v98, 4, v142
	v_ashrrev_i32_e32 v100, 3, v133
	v_and_b32_e32 v98, 0x70, v98
	v_mov_b32_e32 v99, v0
	v_lshl_add_u64 v[102:103], s[2:3], 0, v[98:99]
	v_lshrrev_b32_e32 v99, 2, v100
	v_xor_b32_e32 v99, v99, v142
	v_add_u32_e32 v108, s52, v100
	v_lshlrev_b32_e32 v99, 4, v99
	v_lshlrev_b32_e32 v98, 7, v108
	v_and_b32_e32 v99, 0x70, v99
	s_waitcnt lgkmcnt(0)
	s_barrier
	v_add3_u32 v98, s53, v98, v99
	ds_read_b128 v[150:153], v98
	v_mul_lo_u32 v104, s69, v108
	v_mov_b32_e32 v105, v0
	v_lshl_add_u64 v[166:167], v[104:105], 1, v[102:103]
	s_lshl_b32 s2, s69, 3
	v_add_u32_e32 v104, s2, v104
	v_lshl_add_u64 v[168:169], v[104:105], 1, v[102:103]
	v_add_u32_e32 v98, 8, v108
	v_lshlrev_b32_e32 v99, 7, v98
	v_lshrrev_b32_e32 v98, 2, v98
	v_xor_b32_e32 v98, v98, v142
	v_lshlrev_b32_e32 v98, 4, v98
	v_and_b32_e32 v98, 0x70, v98
	v_add3_u32 v98, s53, v99, v98
	ds_read_b128 v[154:157], v98
	v_add_u32_e32 v104, s2, v104
	s_nop 1
	v_add_u32_e32 v98, 16, v108
	v_lshlrev_b32_e32 v99, 7, v98
	v_lshrrev_b32_e32 v98, 2, v98
	v_xor_b32_e32 v98, v98, v142
	v_lshlrev_b32_e32 v98, 4, v98
	v_and_b32_e32 v98, 0x70, v98
	v_add3_u32 v98, s53, v99, v98
	ds_read_b128 v[158:161], v98
	v_lshl_add_u64 v[170:171], v[104:105], 1, v[102:103]
	v_add_u32_e32 v104, s2, v104
	v_lshl_add_u64 v[172:173], v[104:105], 1, v[102:103]
	s_nop 1
	v_add_u32_e32 v98, 24, v108
	v_lshlrev_b32_e32 v99, 7, v98
	v_lshrrev_b32_e32 v98, 2, v98
	v_xor_b32_e32 v98, v98, v142
	v_lshlrev_b32_e32 v98, 4, v98
	v_and_b32_e32 v98, 0x70, v98
	v_add3_u32 v98, s53, v99, v98
	ds_read_b128 v[162:165], v98
	s_waitcnt lgkmcnt(3)
	global_store_dwordx4 v[166:167], v[150:153], off sc1
	s_waitcnt lgkmcnt(2)
	global_store_dwordx4 v[168:169], v[154:157], off sc1
	s_waitcnt lgkmcnt(1)
	global_store_dwordx4 v[170:171], v[158:161], off sc1
	s_waitcnt lgkmcnt(0)
	global_store_dwordx4 v[172:173], v[162:165], off sc1
	s_waitcnt lgkmcnt(0)
	s_barrier

.LBB0_336:
	v_and_b32_e32 v103, s24, v101
	v_lshlrev_b32_e32 v104, 4, v103
	v_ashrrev_i32_e32 v103, 4, v99
	v_add_u32_e32 v114, s75, v103
	v_xor_b32_e32 v103, v103, v101
	v_mov_b32_e32 v105, v0
	v_lshlrev_b32_e32 v103, 4, v103
	v_lshl_add_u64 v[108:109], s[48:49], 0, v[104:105]
	v_lshlrev_b32_e32 v104, 8, v114
	v_and_b32_e32 v103, 0xf0, v103
	s_waitcnt lgkmcnt(0)
	s_barrier
	v_add3_u32 v103, s53, v103, v104
	ds_read_b128 v[150:153], v103
	v_mul_lo_u32 v110, s5, v114
	v_mov_b32_e32 v111, v0
	v_lshl_add_u64 v[166:167], v[110:111], 1, v[108:109]
	v_add_u32_e32 v103, 4, v114
	s_lshl_b32 s5, s5, 2
	v_add_u32_e32 v110, s5, v110
	v_lshlrev_b32_e32 v104, 8, v103
	v_xor_b32_e32 v103, v103, v101
	v_lshlrev_b32_e32 v103, 4, v103
	v_and_b32_e32 v103, 0xf0, v103
	v_add3_u32 v103, s53, v103, v104
	ds_read_b128 v[154:157], v103
	v_lshl_add_u64 v[168:169], v[110:111], 1, v[108:109]
	v_add_u32_e32 v103, 8, v114
	v_add_u32_e32 v110, s5, v110
	v_lshl_add_u64 v[170:171], v[110:111], 1, v[108:109]
	s_nop 0
	v_lshlrev_b32_e32 v104, 8, v103
	v_xor_b32_e32 v103, v103, v101
	v_lshlrev_b32_e32 v103, 4, v103
	v_and_b32_e32 v103, 0xf0, v103
	v_add3_u32 v103, s53, v103, v104
	ds_read_b128 v[158:161], v103
	v_add_u32_e32 v103, 12, v114
	s_nop 1
	v_add_u32_e32 v104, s5, v110
	v_mov_b32_e32 v105, v0
	v_lshl_add_u64 v[172:173], v[104:105], 1, v[108:109]
	v_lshlrev_b32_e32 v104, 8, v103
	v_xor_b32_e32 v103, v103, v101
	v_lshlrev_b32_e32 v103, 4, v103
	v_and_b32_e32 v103, 0xf0, v103
	v_add3_u32 v103, s53, v103, v104
	ds_read_b128 v[162:165], v103
	s_waitcnt lgkmcnt(3)
	global_store_dwordx4 v[166:167], v[150:153], off sc1
	s_waitcnt lgkmcnt(2)
	global_store_dwordx4 v[168:169], v[154:157], off sc1
	s_waitcnt lgkmcnt(1)
	global_store_dwordx4 v[170:171], v[158:161], off sc1
	s_waitcnt lgkmcnt(0)
	global_store_dwordx4 v[172:173], v[162:165], off sc1
	s_waitcnt lgkmcnt(0)
	s_barrier
	s_cmp_lt_i32 s50, 8
	s_cbranch_scc0 .LBB0_307

.LBB0_352:
	v_lshlrev_b32_e32 v66, 4, v101
	v_ashrrev_i32_e32 v68, 3, v99
	v_and_b32_e32 v66, 0x70, v66
	v_mov_b32_e32 v67, v0
	v_lshl_add_u64 v[70:71], s[48:49], 0, v[66:67]
	v_lshrrev_b32_e32 v67, 2, v68
	v_xor_b32_e32 v67, v67, v101
	v_add_u32_e32 v76, s52, v68
	v_lshlrev_b32_e32 v67, 4, v67
	v_lshlrev_b32_e32 v66, 7, v76
	v_and_b32_e32 v67, 0x70, v67
	s_waitcnt lgkmcnt(0)
	s_barrier
	v_add3_u32 v66, s53, v66, v67
	ds_read_b128 v[150:153], v66
	v_mul_lo_u32 v72, s5, v76
	v_mov_b32_e32 v73, v0
	v_lshl_add_u64 v[166:167], v[72:73], 1, v[70:71]
	s_lshl_b32 s5, s5, 3
	v_add_u32_e32 v72, s5, v72
	v_lshl_add_u64 v[168:169], v[72:73], 1, v[70:71]
	v_add_u32_e32 v66, 8, v76
	v_lshlrev_b32_e32 v67, 7, v66
	v_lshrrev_b32_e32 v66, 2, v66
	v_xor_b32_e32 v66, v66, v101
	v_lshlrev_b32_e32 v66, 4, v66
	v_and_b32_e32 v66, 0x70, v66
	v_add3_u32 v66, s53, v67, v66
	ds_read_b128 v[154:157], v66
	v_add_u32_e32 v72, s5, v72
	s_nop 1
	v_add_u32_e32 v66, 16, v76
	v_lshlrev_b32_e32 v67, 7, v66
	v_lshrrev_b32_e32 v66, 2, v66
	v_xor_b32_e32 v66, v66, v101
	v_lshlrev_b32_e32 v66, 4, v66
	v_and_b32_e32 v66, 0x70, v66
	v_add3_u32 v66, s53, v67, v66
	ds_read_b128 v[158:161], v66
	v_lshl_add_u64 v[170:171], v[72:73], 1, v[70:71]
	v_add_u32_e32 v72, s5, v72
	v_lshl_add_u64 v[172:173], v[72:73], 1, v[70:71]
	s_nop 1
	v_add_u32_e32 v66, 24, v76
	v_lshlrev_b32_e32 v67, 7, v66
	v_lshrrev_b32_e32 v66, 2, v66
	v_xor_b32_e32 v66, v66, v101
	v_lshlrev_b32_e32 v66, 4, v66
	v_and_b32_e32 v66, 0x70, v66
	v_add3_u32 v66, s53, v67, v66
	ds_read_b128 v[162:165], v66
	s_waitcnt lgkmcnt(3)
	global_store_dwordx4 v[166:167], v[150:153], off sc1
	s_waitcnt lgkmcnt(2)
	global_store_dwordx4 v[168:169], v[154:157], off sc1
	s_waitcnt lgkmcnt(1)
	global_store_dwordx4 v[170:171], v[158:161], off sc1
	s_waitcnt lgkmcnt(0)
	global_store_dwordx4 v[172:173], v[162:165], off sc1
	s_waitcnt lgkmcnt(0)
	s_barrier
.LBB0_353:
	s_add_i32 s46, s17, 0x80
	s_lshl_b32 s5, s46, 7
	s_add_i32 s19, s5, 0xffc00000
	v_mov_b32_e32 v78, v1
	v_mov_b32_e32 v79, v249
	s_and_b64 s[48:49], s[10:11], exec
	s_cselect_b32 s24, s19, s5
	v_lshlrev_b32_e32 v66, 2, v79
	v_add_u32_e32 v68, s52, v66
	s_mov_b64 s[48:49], -1
	s_and_b64 vcc, exec, s[60:61]
	v_readlane_b32 s86, v251, 14
	s_cbranch_vccz .LBB0_380
	s_and_b64 vcc, exec, s[0:1]
	s_cbranch_vccnz .LBB0_379
	s_lshl_b32 s5, s46, 6
	s_add_i32 s19, s5, 0xffe00000
	s_mov_b32 s47, s75
	s_and_b64 s[0:1], s[10:11], exec
	v_readlane_b32 s72, v251, 3
	s_cselect_b32 s0, s19, s5
	s_lshl_b32 s48, s46, 3
	v_readlane_b32 s78, v251, 9
	v_readlane_b32 s5, v251, 37
	s_mov_b32 s1, s25
	v_readlane_b32 s79, v251, 10
	s_add_u32 s5, s78, s5
	s_addc_u32 s19, s79, 0
	s_lshl_b64 s[0:1], s[0:1], 2
	s_mov_b32 s49, s25
	s_add_u32 s0, s5, s0
	s_addc_u32 s1, s19, s1
	s_lshl_b64 s[48:49], s[48:49], 2
	v_readlane_b32 s36, v252, 47
	v_readlane_b32 s37, v252, 48
	s_add_u32 s82, s36, s48
	s_addc_u32 s83, s37, s49
	v_readlane_b32 s36, v251, 39
	v_readlane_b32 s73, v251, 4
	v_cmp_gt_i32_e32 vcc, 2, v79
	v_readlane_b32 s37, v251, 40
	v_ashrrev_i32_e32 v67, 31, v66
	s_and_b64 s[48:49], s[36:37], vcc
	v_lshlrev_b32_e32 v70, 3, v78
	v_lshl_add_u64 v[72:73], v[66:67], 2, s[82:83]
	s_mov_b64 s[72:73], -1
	s_and_b64 vcc, exec, s[66:67]
	v_readlane_b32 s74, v251, 5
	v_readlane_b32 s75, v251, 6
	v_readlane_b32 s76, v251, 7
	v_readlane_b32 s77, v251, 8
	s_cbranch_vccz .LBB0_359
	s_and_saveexec_b64 s[72:73], s[48:49]
	s_cbranch_execz .LBB0_358
	s_mov_b32 s36, 0x3d3504f3
	v_mov_b32_e32 v71, v0
	v_pk_mul_f32 v[76:77], v[12:13], s[36:37] op_sel_hi:[1,0]
	v_pk_mul_f32 v[74:75], v[10:11], s[36:37] op_sel_hi:[1,0]
	v_lshl_add_u64 v[80:81], v[70:71], 2, v[72:73]
	global_store_dwordx4 v[80:81], v[74:77], off sc1

.LBB0_361:
	v_cndmask_b32_e64 v67, 0, 1, s[66:67]
	v_cmp_ne_u32_e64 s[0:1], 1, v67
	s_andn2_b64 vcc, exec, s[66:67]
	s_mov_b64 s[66:67], -1
	s_mov_b32 s74, 0xc2fc0000
	s_mov_b32 s75, s47
	s_cbranch_vccnz .LBB0_373
	s_and_saveexec_b64 s[66:67], s[48:49]
	s_cbranch_execz .LBB0_364
	s_mov_b32 s36, 0x3d3504f3
	v_add_u32_e32 v84, 0x80, v70
	v_mov_b32_e32 v85, v0
	v_pk_mul_f32 v[82:83], v[24:25], s[36:37] op_sel_hi:[1,0]
	v_pk_mul_f32 v[80:81], v[22:23], s[36:37] op_sel_hi:[1,0]
	v_lshl_add_u64 v[84:85], v[84:85], 2, v[72:73]
	global_store_dwordx4 v[84:85], v[80:83], off sc1

.LBB0_366:
	s_and_saveexec_b64 s[66:67], s[48:49]
	s_cbranch_execz .LBB0_368
	s_mov_b32 s36, 0x3d3504f3
	v_add_u32_e32 v84, 0x100, v70
	v_mov_b32_e32 v85, v0
	v_pk_mul_f32 v[82:83], v[44:45], s[36:37] op_sel_hi:[1,0]
	v_pk_mul_f32 v[80:81], v[42:43], s[36:37] op_sel_hi:[1,0]
	v_lshl_add_u64 v[84:85], v[84:85], 2, v[72:73]
	global_store_dwordx4 v[84:85], v[80:83], off sc1

.LBB0_370:
	s_and_saveexec_b64 s[0:1], s[48:49]
	s_cbranch_execz .LBB0_372
	s_mov_b32 s36, 0x3d3504f3
	v_add_u32_e32 v70, 0x180, v70
	v_mov_b32_e32 v71, v0
	v_pk_mul_f32 v[82:83], v[56:57], s[36:37] op_sel_hi:[1,0]
	v_pk_mul_f32 v[80:81], v[54:55], s[36:37] op_sel_hi:[1,0]
	v_lshl_add_u64 v[70:71], v[70:71], 2, v[72:73]
	global_store_dwordx4 v[70:71], v[80:83], off sc1

.LBB0_418:
	s_waitcnt lgkmcnt(0)
	s_barrier
	v_and_b32_e32 v70, 15, v78
	v_readlane_b32 s36, v251, 51
	v_cmp_gt_u32_e32 vcc, 8, v70
	v_readlane_b32 s37, v251, 52
	s_or_b64 s[58:59], s[36:37], vcc
	s_and_saveexec_b64 s[46:47], s[58:59]
	s_mov_b32 s74, 0xc2fc0000
	s_mov_b32 s75, s76
	s_cbranch_execz .LBB0_420
	v_lshrrev_b32_e32 v70, 3, v70
	v_mul_u32_u24_e32 v70, s57, v70
	v_and_b32_e32 v71, s54, v78
	v_lshlrev_b32_e32 v70, 1, v70
	v_lshl_or_b32 v70, v71, 4, v70
	v_mov_b32_e32 v71, v0
	v_lshl_add_u64 v[74:75], s[70:71], 0, v[70:71]
	v_ashrrev_i32_e32 v70, 4, v67
	v_add_u32_e32 v79, s75, v70
	v_xor_b32_e32 v70, v70, v78
	v_lshlrev_b32_e32 v70, 4, v70
	v_lshlrev_b32_e32 v71, 8, v79
	v_and_b32_e32 v70, 0xf0, v70
	v_add3_u32 v70, s53, v70, v71
	ds_read_b128 v[150:153], v70
	v_mul_lo_u32 v76, s51, v79
	v_mov_b32_e32 v77, v0
	v_lshl_add_u64 v[166:167], v[76:77], 1, v[74:75]
	s_lshl_b32 s19, s51, 2
	v_add_u32_e32 v76, s19, v76
	v_lshl_add_u64 v[168:169], v[76:77], 1, v[74:75]
	v_add_u32_e32 v70, 4, v79
	v_lshlrev_b32_e32 v71, 8, v70
	v_xor_b32_e32 v70, v70, v78
	v_lshlrev_b32_e32 v70, 4, v70
	v_and_b32_e32 v70, 0xf0, v70
	v_add3_u32 v70, s53, v70, v71
	ds_read_b128 v[154:157], v70
	v_add_u32_e32 v76, s19, v76
	s_nop 1
	v_add_u32_e32 v70, 8, v79
	v_lshlrev_b32_e32 v71, 8, v70
	v_xor_b32_e32 v70, v70, v78
	v_lshlrev_b32_e32 v70, 4, v70
	v_and_b32_e32 v70, 0xf0, v70
	v_add3_u32 v70, s53, v70, v71
	ds_read_b128 v[158:161], v70
	v_lshl_add_u64 v[170:171], v[76:77], 1, v[74:75]
	s_nop 1
	v_add_u32_e32 v72, 12, v79
	v_add_u32_e32 v70, s19, v76
	v_mov_b32_e32 v71, v0
	v_lshl_add_u64 v[172:173], v[70:71], 1, v[74:75]
	v_xor_b32_e32 v71, v72, v78
	v_lshlrev_b32_e32 v71, 4, v71
	v_lshlrev_b32_e32 v70, 8, v72
	v_and_b32_e32 v71, 0xf0, v71
	v_add3_u32 v70, s53, v71, v70
	ds_read_b128 v[162:165], v70
	s_waitcnt lgkmcnt(3)
	global_store_dwordx4 v[166:167], v[150:153], off sc1
	s_waitcnt lgkmcnt(2)
	global_store_dwordx4 v[168:169], v[154:157], off sc1
	s_waitcnt lgkmcnt(1)
	global_store_dwordx4 v[170:171], v[158:161], off sc1
	s_waitcnt lgkmcnt(0)
	global_store_dwordx4 v[172:173], v[162:165], off sc1

.LBB0_433:
	v_lshlrev_b32_e32 v10, 4, v78
	v_ashrrev_i32_e32 v12, 3, v67
	v_and_b32_e32 v10, 0x70, v10
	v_mov_b32_e32 v11, v0
	v_lshl_add_u64 v[22:23], s[6:7], 0, v[10:11]
	v_lshrrev_b32_e32 v11, 2, v12
	v_xor_b32_e32 v11, v11, v78
	v_add_u32_e32 v32, s52, v12
	v_lshlrev_b32_e32 v11, 4, v11
	v_lshlrev_b32_e32 v10, 7, v32
	v_and_b32_e32 v11, 0x70, v11
	s_waitcnt lgkmcnt(0)
	s_barrier
	v_add3_u32 v10, s53, v10, v11
	ds_read_b128 v[150:153], v10
	v_mul_lo_u32 v24, s5, v32
	v_mov_b32_e32 v25, v0
	v_lshl_add_u64 v[166:167], v[24:25], 1, v[22:23]
	s_lshl_b32 s5, s5, 3
	v_add_u32_e32 v24, s5, v24
	v_lshl_add_u64 v[168:169], v[24:25], 1, v[22:23]
	v_add_u32_e32 v10, 8, v32
	v_lshlrev_b32_e32 v11, 7, v10
	v_lshrrev_b32_e32 v10, 2, v10
	v_xor_b32_e32 v10, v10, v78
	v_lshlrev_b32_e32 v10, 4, v10
	v_and_b32_e32 v10, 0x70, v10
	v_add3_u32 v10, s53, v11, v10
	ds_read_b128 v[154:157], v10
	v_add_u32_e32 v24, s5, v24
	s_nop 1
	v_add_u32_e32 v10, 16, v32
	v_lshlrev_b32_e32 v11, 7, v10
	v_lshrrev_b32_e32 v10, 2, v10
	v_xor_b32_e32 v10, v10, v78
	v_lshlrev_b32_e32 v10, 4, v10
	v_and_b32_e32 v10, 0x70, v10
	v_add3_u32 v10, s53, v11, v10
	ds_read_b128 v[158:161], v10
	v_lshl_add_u64 v[170:171], v[24:25], 1, v[22:23]
	v_add_u32_e32 v24, s5, v24
	v_lshl_add_u64 v[172:173], v[24:25], 1, v[22:23]
	s_nop 1
	v_add_u32_e32 v10, 24, v32
	v_lshlrev_b32_e32 v11, 7, v10
	v_lshrrev_b32_e32 v10, 2, v10
	v_xor_b32_e32 v10, v10, v78
	v_lshlrev_b32_e32 v10, 4, v10
	v_and_b32_e32 v10, 0x70, v10
	v_add3_u32 v10, s53, v11, v10
	ds_read_b128 v[162:165], v10
	s_waitcnt lgkmcnt(3)
	global_store_dwordx4 v[166:167], v[150:153], off sc1
	s_waitcnt lgkmcnt(2)
	global_store_dwordx4 v[168:169], v[154:157], off sc1
	s_waitcnt lgkmcnt(1)
	global_store_dwordx4 v[170:171], v[158:161], off sc1
	s_waitcnt lgkmcnt(0)
	global_store_dwordx4 v[172:173], v[162:165], off sc1
	s_waitcnt lgkmcnt(0)
	s_barrier

.LBB0_467:
	v_and_b32_e32 v13, s5, v1
	v_lshlrev_b32_e32 v22, 4, v13
	v_ashrrev_i32_e32 v13, 4, v11
	v_add_u32_e32 v44, s75, v13
	v_xor_b32_e32 v13, v13, v1
	v_mov_b32_e32 v23, v0
	v_lshlrev_b32_e32 v13, 4, v13
	v_lshl_add_u64 v[30:31], s[2:3], 0, v[22:23]
	v_lshlrev_b32_e32 v22, 8, v44
	v_and_b32_e32 v13, 0xf0, v13
	s_waitcnt lgkmcnt(0)
	s_barrier
	v_add3_u32 v13, s53, v13, v22
	ds_read_b128 v[150:153], v13
	v_mul_lo_u32 v32, s4, v44
	v_mov_b32_e32 v33, v0
	v_lshl_add_u64 v[166:167], v[32:33], 1, v[30:31]
	v_add_u32_e32 v13, 4, v44
	s_lshl_b32 s2, s4, 2
	v_add_u32_e32 v32, s2, v32
	v_lshlrev_b32_e32 v22, 8, v13
	v_xor_b32_e32 v13, v13, v1
	v_lshlrev_b32_e32 v13, 4, v13
	v_and_b32_e32 v13, 0xf0, v13
	v_add3_u32 v13, s53, v13, v22
	ds_read_b128 v[154:157], v13
	v_lshl_add_u64 v[168:169], v[32:33], 1, v[30:31]
	v_add_u32_e32 v13, 8, v44
	v_add_u32_e32 v32, s2, v32
	v_lshl_add_u64 v[170:171], v[32:33], 1, v[30:31]
	s_nop 0
	v_lshlrev_b32_e32 v22, 8, v13
	v_xor_b32_e32 v13, v13, v1
	v_lshlrev_b32_e32 v13, 4, v13
	v_and_b32_e32 v13, 0xf0, v13
	v_add3_u32 v13, s53, v13, v22
	ds_read_b128 v[158:161], v13
	v_add_u32_e32 v13, 12, v44
	s_nop 1
	v_add_u32_e32 v22, s2, v32
	v_mov_b32_e32 v23, v0
	v_lshl_add_u64 v[172:173], v[22:23], 1, v[30:31]
	v_lshlrev_b32_e32 v22, 8, v13
	v_xor_b32_e32 v13, v13, v1
	v_lshlrev_b32_e32 v13, 4, v13
	v_and_b32_e32 v13, 0xf0, v13
	v_add3_u32 v13, s53, v13, v22
	ds_read_b128 v[162:165], v13
	s_waitcnt lgkmcnt(3)
	global_store_dwordx4 v[166:167], v[150:153], off sc1
	s_waitcnt lgkmcnt(2)
	global_store_dwordx4 v[168:169], v[154:157], off sc1
	s_waitcnt lgkmcnt(1)
	global_store_dwordx4 v[170:171], v[158:161], off sc1
	s_waitcnt lgkmcnt(0)
	global_store_dwordx4 v[172:173], v[162:165], off sc1
	s_waitcnt lgkmcnt(0)
	s_barrier
	s_cmp_lt_i32 s50, 8
	s_cbranch_scc0 .LBB0_438

.LBB0_983:
	ds_read_b128 v[148:151], v143
	ds_read_b128 v[152:155], v143 offset:1024
	ds_read_b128 v[156:159], v143 offset:2048
	ds_read_b128 v[160:163], v143 offset:3072
	s_add_u32 s22, s20, 0xfffc0080
	s_addc_u32 s23, s21, -1
	s_cmp_eq_u32 s50, 12
	s_cselect_b32 s25, s9, s23
	s_cselect_b32 s24, s46, s22
	s_cselect_b32 s23, s15, s49
	s_cselect_b32 s22, s47, s48
	s_mov_b32 m0, s42
	v_lshl_add_u64 v[196:197], s[20:21], 0, v[134:135]
	ds_read_b128 v[164:167], v142
	ds_read_b128 v[168:171], v142 offset:1024
	ds_read_b128 v[172:175], v142 offset:2048
	ds_read_b128 v[176:179], v142 offset:3072
	ds_read_b128 v[180:183], v142 offset:4096
	ds_read_b128 v[184:187], v142 offset:5120
	ds_read_b128 v[188:191], v142 offset:6144
	ds_read_b128 v[192:195], v142 offset:7168
	global_load_lds_dwordx4 v[196:197], off
	v_lshl_add_u64 v[196:197], s[20:21], 0, v[136:137]
	s_mov_b32 m0, s43
	s_nop 0
	global_load_lds_dwordx4 v[196:197], off
	s_waitcnt lgkmcnt(8)
	s_barrier
	s_waitcnt lgkmcnt(0)
	s_setprio 1
	s_waitcnt lgkmcnt(0)
	v_mfma_f32_16x16x32_bf16 v[124:127], v[148:151], v[164:167], v[124:127]
	v_mfma_f32_16x16x32_bf16 v[120:123], v[156:159], v[164:167], v[120:123]
	v_mfma_f32_16x16x32_bf16 v[116:119], v[148:151], v[172:175], v[116:119]
	v_mfma_f32_16x16x32_bf16 v[112:115], v[156:159], v[172:175], v[112:115]
	v_mfma_f32_16x16x32_bf16 v[108:111], v[148:151], v[180:183], v[108:111]
	v_mfma_f32_16x16x32_bf16 v[104:107], v[156:159], v[180:183], v[104:107]
	v_mfma_f32_16x16x32_bf16 v[100:103], v[148:151], v[188:191], v[100:103]
	v_mfma_f32_16x16x32_bf16 v[96:99], v[156:159], v[188:191], v[96:99]
	v_mfma_f32_16x16x32_bf16 v[124:127], v[152:155], v[168:171], v[124:127]
	v_mfma_f32_16x16x32_bf16 v[120:123], v[160:163], v[168:171], v[120:123]
	v_mfma_f32_16x16x32_bf16 v[116:119], v[152:155], v[176:179], v[116:119]
	v_mfma_f32_16x16x32_bf16 v[112:115], v[160:163], v[176:179], v[112:115]
	v_mfma_f32_16x16x32_bf16 v[108:111], v[152:155], v[184:187], v[108:111]
	v_mfma_f32_16x16x32_bf16 v[104:107], v[160:163], v[184:187], v[104:107]
	v_mfma_f32_16x16x32_bf16 v[100:103], v[152:155], v[192:195], v[100:103]
	v_mfma_f32_16x16x32_bf16 v[96:99], v[160:163], v[192:195], v[96:99]
	s_setprio 0
	s_barrier
	s_mov_b32 m0, s27
	v_lshl_add_u64 v[196:197], s[22:23], 0, v[130:131]
	ds_read_b128 v[200:203], v144
	ds_read_b128 v[204:207], v144 offset:1024
	ds_read_b128 v[208:211], v144 offset:2048
	ds_read_b128 v[212:215], v144 offset:3072
	global_load_lds_dwordx4 v[196:197], off
	v_lshl_add_u64 v[216:217], s[22:23], 0, v[128:129]
	s_mov_b32 m0, s28
	s_nop 0
	global_load_lds_dwordx4 v[216:217], off
	s_barrier
	s_waitcnt lgkmcnt(0)
	s_setprio 1
	s_waitcnt lgkmcnt(0)
	v_mfma_f32_16x16x32_bf16 v[92:95], v[200:203], v[164:167], v[92:95]
	v_mfma_f32_16x16x32_bf16 v[88:91], v[208:211], v[164:167], v[88:91]
	v_mfma_f32_16x16x32_bf16 v[84:87], v[200:203], v[172:175], v[84:87]
	v_mfma_f32_16x16x32_bf16 v[80:83], v[208:211], v[172:175], v[80:83]
	v_mfma_f32_16x16x32_bf16 v[76:79], v[200:203], v[180:183], v[76:79]
	v_mfma_f32_16x16x32_bf16 v[72:75], v[208:211], v[180:183], v[72:75]
	v_mfma_f32_16x16x32_bf16 v[68:71], v[200:203], v[188:191], v[68:71]
	v_mfma_f32_16x16x32_bf16 v[64:67], v[208:211], v[188:191], v[64:67]
	v_mfma_f32_16x16x32_bf16 v[92:95], v[204:207], v[168:171], v[92:95]
	v_mfma_f32_16x16x32_bf16 v[88:91], v[212:215], v[168:171], v[88:91]
	v_mfma_f32_16x16x32_bf16 v[84:87], v[204:207], v[176:179], v[84:87]
	v_mfma_f32_16x16x32_bf16 v[80:83], v[212:215], v[176:179], v[80:83]
	v_mfma_f32_16x16x32_bf16 v[76:79], v[204:207], v[184:187], v[76:79]
	v_mfma_f32_16x16x32_bf16 v[72:75], v[212:215], v[184:187], v[72:75]
	v_mfma_f32_16x16x32_bf16 v[68:71], v[204:207], v[192:195], v[68:71]
	v_mfma_f32_16x16x32_bf16 v[64:67], v[212:215], v[192:195], v[64:67]
	s_setprio 0
	s_mov_b32 m0, s86
	v_lshl_add_u64 v[218:219], s[24:25], 0, v[130:131]
	s_barrier
	ds_read_b128 v[164:167], v142 offset:16384
	ds_read_b128 v[168:171], v142 offset:17408
	ds_read_b128 v[172:175], v142 offset:18432
	ds_read_b128 v[176:179], v142 offset:19456
	ds_read_b128 v[180:183], v142 offset:20480
	ds_read_b128 v[184:187], v142 offset:21504
	ds_read_b128 v[188:191], v142 offset:22528
	ds_read_b128 v[192:195], v142 offset:23552
	global_load_lds_dwordx4 v[218:219], off
	v_lshl_add_u64 v[220:221], s[24:25], 0, v[128:129]
	s_mov_b32 m0, s29
	s_nop 0
	global_load_lds_dwordx4 v[220:221], off
	s_barrier
	s_waitcnt lgkmcnt(0)
	s_setprio 1
	s_waitcnt lgkmcnt(0)
	v_mfma_f32_16x16x32_bf16 v[60:63], v[148:151], v[164:167], v[60:63]
	v_mfma_f32_16x16x32_bf16 v[56:59], v[156:159], v[164:167], v[56:59]
	v_mfma_f32_16x16x32_bf16 v[52:55], v[148:151], v[172:175], v[52:55]
	v_mfma_f32_16x16x32_bf16 v[48:51], v[156:159], v[172:175], v[48:51]
	v_mfma_f32_16x16x32_bf16 v[44:47], v[148:151], v[180:183], v[44:47]
	v_mfma_f32_16x16x32_bf16 v[40:43], v[156:159], v[180:183], v[40:43]
	v_mfma_f32_16x16x32_bf16 v[36:39], v[148:151], v[188:191], v[36:39]
	v_mfma_f32_16x16x32_bf16 v[32:35], v[156:159], v[188:191], v[32:35]
	v_mfma_f32_16x16x32_bf16 v[60:63], v[152:155], v[168:171], v[60:63]
	v_mfma_f32_16x16x32_bf16 v[56:59], v[160:163], v[168:171], v[56:59]
	v_mfma_f32_16x16x32_bf16 v[52:55], v[152:155], v[176:179], v[52:55]
	v_mfma_f32_16x16x32_bf16 v[48:51], v[160:163], v[176:179], v[48:51]
	v_mfma_f32_16x16x32_bf16 v[44:47], v[152:155], v[184:187], v[44:47]
	v_mfma_f32_16x16x32_bf16 v[40:43], v[160:163], v[184:187], v[40:43]
	v_mfma_f32_16x16x32_bf16 v[36:39], v[152:155], v[192:195], v[36:39]
	v_mfma_f32_16x16x32_bf16 v[32:35], v[160:163], v[192:195], v[32:35]
	s_setprio 0
	s_barrier
	s_add_u32 s52, s22, 0x40000
	s_addc_u32 s53, s23, 0
	s_mov_b32 m0, s30
	v_lshl_add_u64 v[148:149], s[52:53], 0, v[130:131]
	global_load_lds_dwordx4 v[148:149], off
	v_lshl_add_u64 v[148:149], s[52:53], 0, v[128:129]
	s_mov_b32 m0, s31
	s_nop 0
	global_load_lds_dwordx4 v[148:149], off
	s_waitcnt vmcnt(6)
	s_barrier
	s_setprio 1
	v_mfma_f32_16x16x32_bf16 v[28:31], v[200:203], v[164:167], v[28:31]
	v_mfma_f32_16x16x32_bf16 v[24:27], v[208:211], v[164:167], v[24:27]
	v_mfma_f32_16x16x32_bf16 v[20:23], v[200:203], v[172:175], v[20:23]
	v_mfma_f32_16x16x32_bf16 v[16:19], v[208:211], v[172:175], v[16:19]
	v_mfma_f32_16x16x32_bf16 v[12:15], v[200:203], v[180:183], v[12:15]
	v_mfma_f32_16x16x32_bf16 v[8:11], v[208:211], v[180:183], v[8:11]
	v_mfma_f32_16x16x32_bf16 v[4:7], v[200:203], v[188:191], v[4:7]
	v_mfma_f32_16x16x32_bf16 v[0:3], v[208:211], v[188:191], v[0:3]
	v_mfma_f32_16x16x32_bf16 v[28:31], v[204:207], v[168:171], v[28:31]
	v_mfma_f32_16x16x32_bf16 v[24:27], v[212:215], v[168:171], v[24:27]
	v_mfma_f32_16x16x32_bf16 v[20:23], v[204:207], v[176:179], v[20:23]
	v_mfma_f32_16x16x32_bf16 v[16:19], v[212:215], v[176:179], v[16:19]
	v_mfma_f32_16x16x32_bf16 v[12:15], v[204:207], v[184:187], v[12:15]
	v_mfma_f32_16x16x32_bf16 v[8:11], v[212:215], v[184:187], v[8:11]
	v_mfma_f32_16x16x32_bf16 v[4:7], v[204:207], v[192:195], v[4:7]
	v_mfma_f32_16x16x32_bf16 v[0:3], v[212:215], v[192:195], v[0:3]
	s_setprio 0
	s_barrier
	ds_read_b128 v[148:151], v145
	ds_read_b128 v[152:155], v145 offset:1024
	ds_read_b128 v[156:159], v145 offset:2048
	ds_read_b128 v[160:163], v145 offset:3072
	s_add_u32 s24, s24, 0x40000
	s_addc_u32 s25, s25, 0
	s_mov_b32 m0, s33
	v_lshl_add_u64 v[200:201], s[24:25], 0, v[130:131]
	ds_read_b128 v[164:167], v142 offset:32768
	ds_read_b128 v[168:171], v142 offset:33792
	ds_read_b128 v[172:175], v142 offset:34816
	ds_read_b128 v[176:179], v142 offset:35840
	ds_read_b128 v[180:183], v142 offset:36864
	ds_read_b128 v[184:187], v142 offset:37888
	ds_read_b128 v[188:191], v142 offset:38912
	ds_read_b128 v[192:195], v142 offset:39936
	global_load_lds_dwordx4 v[200:201], off
	v_lshl_add_u64 v[200:201], s[24:25], 0, v[128:129]
	s_mov_b32 m0, s34
	s_nop 0
	global_load_lds_dwordx4 v[200:201], off
	s_waitcnt lgkmcnt(8)
	s_barrier
	s_waitcnt lgkmcnt(0)
	s_setprio 1
	s_waitcnt lgkmcnt(0)
	v_mfma_f32_16x16x32_bf16 v[124:127], v[148:151], v[164:167], v[124:127]
	v_mfma_f32_16x16x32_bf16 v[120:123], v[156:159], v[164:167], v[120:123]
	v_mfma_f32_16x16x32_bf16 v[116:119], v[148:151], v[172:175], v[116:119]
	v_mfma_f32_16x16x32_bf16 v[112:115], v[156:159], v[172:175], v[112:115]
	v_mfma_f32_16x16x32_bf16 v[108:111], v[148:151], v[180:183], v[108:111]
	v_mfma_f32_16x16x32_bf16 v[104:107], v[156:159], v[180:183], v[104:107]
	v_mfma_f32_16x16x32_bf16 v[100:103], v[148:151], v[188:191], v[100:103]
	v_mfma_f32_16x16x32_bf16 v[96:99], v[156:159], v[188:191], v[96:99]
	v_mfma_f32_16x16x32_bf16 v[124:127], v[152:155], v[168:171], v[124:127]
	v_mfma_f32_16x16x32_bf16 v[120:123], v[160:163], v[168:171], v[120:123]
	v_mfma_f32_16x16x32_bf16 v[116:119], v[152:155], v[176:179], v[116:119]
	v_mfma_f32_16x16x32_bf16 v[112:115], v[160:163], v[176:179], v[112:115]
	v_mfma_f32_16x16x32_bf16 v[108:111], v[152:155], v[184:187], v[108:111]
	v_mfma_f32_16x16x32_bf16 v[104:107], v[160:163], v[184:187], v[104:107]
	v_mfma_f32_16x16x32_bf16 v[100:103], v[152:155], v[192:195], v[100:103]
	v_mfma_f32_16x16x32_bf16 v[96:99], v[160:163], v[192:195], v[96:99]
	s_setprio 0
	s_barrier
	s_mov_b32 m0, s36
	v_lshl_add_u64 v[196:197], v[196:197], 0, s[6:7]
	ds_read_b128 v[200:203], v146
	ds_read_b128 v[204:207], v146 offset:1024
	ds_read_b128 v[208:211], v146 offset:2048
	ds_read_b128 v[212:215], v146 offset:3072
	global_load_lds_dwordx4 v[196:197], off
	v_lshl_add_u64 v[196:197], v[216:217], 0, s[6:7]
	s_mov_b32 m0, s37
	s_nop 0
	global_load_lds_dwordx4 v[196:197], off
	s_barrier
	s_waitcnt lgkmcnt(0)
	s_setprio 1
	s_waitcnt lgkmcnt(0)
	v_mfma_f32_16x16x32_bf16 v[92:95], v[200:203], v[164:167], v[92:95]
	v_mfma_f32_16x16x32_bf16 v[88:91], v[208:211], v[164:167], v[88:91]
	v_mfma_f32_16x16x32_bf16 v[84:87], v[200:203], v[172:175], v[84:87]
	v_mfma_f32_16x16x32_bf16 v[80:83], v[208:211], v[172:175], v[80:83]
	v_mfma_f32_16x16x32_bf16 v[76:79], v[200:203], v[180:183], v[76:79]
	v_mfma_f32_16x16x32_bf16 v[72:75], v[208:211], v[180:183], v[72:75]
	v_mfma_f32_16x16x32_bf16 v[68:71], v[200:203], v[188:191], v[68:71]
	v_mfma_f32_16x16x32_bf16 v[64:67], v[208:211], v[188:191], v[64:67]
	v_mfma_f32_16x16x32_bf16 v[92:95], v[204:207], v[168:171], v[92:95]
	v_mfma_f32_16x16x32_bf16 v[88:91], v[212:215], v[168:171], v[88:91]
	v_mfma_f32_16x16x32_bf16 v[84:87], v[204:207], v[176:179], v[84:87]
	v_mfma_f32_16x16x32_bf16 v[80:83], v[212:215], v[176:179], v[80:83]
	v_mfma_f32_16x16x32_bf16 v[76:79], v[204:207], v[184:187], v[76:79]
	v_mfma_f32_16x16x32_bf16 v[72:75], v[212:215], v[184:187], v[72:75]
	v_mfma_f32_16x16x32_bf16 v[68:71], v[204:207], v[192:195], v[68:71]
	v_mfma_f32_16x16x32_bf16 v[64:67], v[212:215], v[192:195], v[64:67]
	s_setprio 0
	s_mov_b32 m0, s38
	v_lshl_add_u64 v[196:197], v[218:219], 0, s[6:7]
	s_barrier
	ds_read_b128 v[164:167], v142 offset:49152
	ds_read_b128 v[168:171], v142 offset:50176
	ds_read_b128 v[172:175], v142 offset:51200
	ds_read_b128 v[176:179], v142 offset:52224
	ds_read_b128 v[180:183], v142 offset:53248
	ds_read_b128 v[184:187], v142 offset:54272
	ds_read_b128 v[188:191], v142 offset:55296
	ds_read_b128 v[192:195], v142 offset:56320
	global_load_lds_dwordx4 v[196:197], off
	v_lshl_add_u64 v[196:197], v[220:221], 0, s[6:7]
	s_mov_b32 m0, s39
	s_nop 0
	global_load_lds_dwordx4 v[196:197], off
	s_barrier
	s_waitcnt lgkmcnt(0)
	s_setprio 1
	s_waitcnt lgkmcnt(0)
	v_mfma_f32_16x16x32_bf16 v[60:63], v[148:151], v[164:167], v[60:63]
	v_mfma_f32_16x16x32_bf16 v[56:59], v[156:159], v[164:167], v[56:59]
	v_mfma_f32_16x16x32_bf16 v[52:55], v[148:151], v[172:175], v[52:55]
	v_mfma_f32_16x16x32_bf16 v[48:51], v[156:159], v[172:175], v[48:51]
	v_mfma_f32_16x16x32_bf16 v[44:47], v[148:151], v[180:183], v[44:47]
	v_mfma_f32_16x16x32_bf16 v[40:43], v[156:159], v[180:183], v[40:43]
	v_mfma_f32_16x16x32_bf16 v[36:39], v[148:151], v[188:191], v[36:39]
	v_mfma_f32_16x16x32_bf16 v[32:35], v[156:159], v[188:191], v[32:35]
	v_mfma_f32_16x16x32_bf16 v[60:63], v[152:155], v[168:171], v[60:63]
	v_mfma_f32_16x16x32_bf16 v[56:59], v[160:163], v[168:171], v[56:59]
	v_mfma_f32_16x16x32_bf16 v[52:55], v[152:155], v[176:179], v[52:55]
	v_mfma_f32_16x16x32_bf16 v[48:51], v[160:163], v[176:179], v[48:51]
	v_mfma_f32_16x16x32_bf16 v[44:47], v[152:155], v[184:187], v[44:47]
	v_mfma_f32_16x16x32_bf16 v[40:43], v[160:163], v[184:187], v[40:43]
	v_mfma_f32_16x16x32_bf16 v[36:39], v[152:155], v[192:195], v[36:39]
	v_mfma_f32_16x16x32_bf16 v[32:35], v[160:163], v[192:195], v[32:35]
	s_setprio 0
	s_barrier
	s_add_u32 s22, s22, 0x40080
	s_addc_u32 s23, s23, 0
	s_mov_b32 m0, s40
	v_lshl_add_u64 v[148:149], s[22:23], 0, v[130:131]
	global_load_lds_dwordx4 v[148:149], off
	v_lshl_add_u64 v[148:149], s[22:23], 0, v[128:129]
	s_mov_b32 m0, s41
	s_nop 0
	global_load_lds_dwordx4 v[148:149], off
	s_waitcnt vmcnt(6)
	s_barrier
	s_setprio 1
	v_mfma_f32_16x16x32_bf16 v[28:31], v[200:203], v[164:167], v[28:31]
	v_mfma_f32_16x16x32_bf16 v[24:27], v[208:211], v[164:167], v[24:27]
	v_mfma_f32_16x16x32_bf16 v[20:23], v[200:203], v[172:175], v[20:23]
	v_mfma_f32_16x16x32_bf16 v[16:19], v[208:211], v[172:175], v[16:19]
	v_mfma_f32_16x16x32_bf16 v[12:15], v[200:203], v[180:183], v[12:15]
	v_mfma_f32_16x16x32_bf16 v[8:11], v[208:211], v[180:183], v[8:11]
	v_mfma_f32_16x16x32_bf16 v[4:7], v[200:203], v[188:191], v[4:7]
	v_mfma_f32_16x16x32_bf16 v[0:3], v[208:211], v[188:191], v[0:3]
	v_mfma_f32_16x16x32_bf16 v[28:31], v[204:207], v[168:171], v[28:31]
	v_mfma_f32_16x16x32_bf16 v[24:27], v[212:215], v[168:171], v[24:27]
	v_mfma_f32_16x16x32_bf16 v[20:23], v[204:207], v[176:179], v[20:23]
	v_mfma_f32_16x16x32_bf16 v[16:19], v[212:215], v[176:179], v[16:19]
	v_mfma_f32_16x16x32_bf16 v[12:15], v[204:207], v[184:187], v[12:15]
	v_mfma_f32_16x16x32_bf16 v[8:11], v[212:215], v[184:187], v[8:11]
	v_mfma_f32_16x16x32_bf16 v[4:7], v[204:207], v[192:195], v[4:7]
	v_mfma_f32_16x16x32_bf16 v[0:3], v[212:215], v[192:195], v[0:3]
	s_setprio 0
	s_add_i32 s50, s50, 2
	s_add_u32 s20, s20, 0x100
	s_addc_u32 s21, s21, 0
	s_add_u32 s48, s48, 0x100
	s_addc_u32 s49, s49, 0
	s_cmp_gt_u32 s50, 13
	s_barrier
	s_cbranch_scc0 .LBB0_983
	v_mov_b32_e32 v147, v198
	v_readlane_b32 s9, v252, 43
	v_readlane_b32 s15, v252, 45
	v_cvt_pk_bf16_f32 v124, v124, v125
	v_ashrrev_i32_e32 v149, 4, v147
	v_and_b32_e32 v132, 15, v147
	v_lshl_add_u32 v156, s9, 4, v149
	s_lshl_b32 s9, s9, 6
	v_lshlrev_b32_e32 v161, 8, v132
	v_lshlrev_b32_e32 v148, 4, v132
	v_lshl_add_u32 v132, v149, 3, s9
	v_xor_b32_e32 v162, v132, v148
	v_add_u32_e32 v132, 32, v132
	v_xor_b32_e32 v163, v132, v148
	v_xor_b32_e32 v132, v149, v147
	v_lshlrev_b32_e32 v132, 4, v132
	v_add_u32_e32 v149, 4, v156
	v_add_u32_e32 v160, 8, v156
	v_cvt_pk_bf16_f32 v125, v126, v127
	v_add3_u32 v126, s35, v162, v161
	v_cvt_pk_bf16_f32 v120, v120, v121
	v_cvt_pk_bf16_f32 v121, v122, v123
	v_add3_u32 v122, s35, v163, v161
	v_cvt_pk_bf16_f32 v116, v116, v117
	v_cvt_pk_bf16_f32 v117, v118, v119
	v_cvt_pk_bf16_f32 v112, v112, v113
	v_cvt_pk_bf16_f32 v113, v114, v115
	v_cvt_pk_bf16_f32 v108, v108, v109
	v_cvt_pk_bf16_f32 v109, v110, v111
	v_cvt_pk_bf16_f32 v104, v104, v105
	v_cvt_pk_bf16_f32 v105, v106, v107
	v_cvt_pk_bf16_f32 v100, v100, v101
	v_cvt_pk_bf16_f32 v101, v102, v103
	v_cvt_pk_bf16_f32 v96, v96, v97
	v_cvt_pk_bf16_f32 v97, v98, v99
	s_lshl_b32 s20, s4, 8
	s_lshl_b32 s15, s15, 6
	v_lshlrev_b32_e32 v164, 8, v156
	v_and_b32_e32 v165, 0xf0, v132
	v_xor_b32_e32 v150, v149, v147
	v_xor_b32_e32 v152, v160, v147
	ds_write_b64 v126, v[124:125]
	ds_write_b64 v122, v[120:121]
	ds_write_b64 v126, v[116:117] offset:4096
	ds_write_b64 v122, v[112:113] offset:4096
	ds_write_b64 v126, v[108:109] offset:8192
	ds_write_b64 v122, v[104:105] offset:8192
	ds_write_b64 v126, v[100:101] offset:12288
	ds_write_b64 v122, v[96:97] offset:12288
	s_add_i32 s15, s15, s20
	v_lshlrev_b32_e32 v150, 4, v150
	v_lshlrev_b32_e32 v152, 4, v152
	v_add_u32_e32 v170, 12, v156
	s_waitcnt lgkmcnt(0)
	s_barrier
	v_add3_u32 v114, s35, v165, v164
	v_add_lshl_u32 v132, s15, v156, 10
	v_and_b32_e32 v167, 0xf0, v150
	v_add_lshl_u32 v150, v149, s15, 10
	v_and_b32_e32 v169, 0xf0, v152
	v_add_lshl_u32 v152, v160, s15, 10
	v_add_lshl_u32 v154, v170, s15, 10
	s_addk_i32 s15, 0x80
	ds_read_b128 v[96:99], v114
	v_lshlrev_b32_e32 v166, 8, v149
	v_add_lshl_u32 v158, s15, v149, 10
	v_mov_b32_e32 v149, v133
	s_lshl_b32 s4, s45, 8
	v_xor_b32_e32 v147, v170, v147
	v_lshl_add_u64 v[148:149], s[10:11], 0, v[148:149]
	v_lshlrev_b32_e32 v168, 8, v160
	v_lshlrev_b32_e32 v147, 4, v147
	v_lshl_add_u64 v[108:109], s[4:5], 1, v[148:149]
	v_add3_u32 v115, s35, v167, v166
	v_lshlrev_b32_e32 v171, 8, v170
	v_and_b32_e32 v147, 0xf0, v147
	v_lshl_add_u64 v[110:111], v[132:133], 1, v[108:109]
	ds_read_b128 v[100:103], v115
	v_add3_u32 v116, s35, v169, v168
	s_waitcnt lgkmcnt(0)
	global_store_dwordx4 v[110:111], v[96:99], off sc1
	ds_read_b128 v[96:99], v116
	v_add3_u32 v117, s35, v147, v171
	ds_read_b128 v[104:107], v117
	v_mov_b32_e32 v151, v133
	v_mov_b32_e32 v153, v133
	v_lshl_add_u64 v[112:113], v[150:151], 1, v[108:109]
	v_mov_b32_e32 v155, v133
	global_store_dwordx4 v[112:113], v[100:103], off sc1
	v_cvt_pk_bf16_f32 v92, v92, v93
	v_cvt_pk_bf16_f32 v93, v94, v95
	v_lshl_add_u64 v[100:101], v[152:153], 1, v[108:109]
	s_waitcnt lgkmcnt(0)
	global_store_dwordx4 v[100:101], v[96:99], off sc1
	v_cvt_pk_bf16_f32 v88, v88, v89
	v_cvt_pk_bf16_f32 v89, v90, v91
	v_lshl_add_u64 v[96:97], v[154:155], 1, v[108:109]
	global_store_dwordx4 v[96:97], v[104:107], off sc1
	v_cvt_pk_bf16_f32 v84, v84, v85
	v_cvt_pk_bf16_f32 v85, v86, v87
	v_cvt_pk_bf16_f32 v80, v80, v81
	v_cvt_pk_bf16_f32 v81, v82, v83
	v_cvt_pk_bf16_f32 v76, v76, v77
	v_cvt_pk_bf16_f32 v77, v78, v79
	v_cvt_pk_bf16_f32 v72, v72, v73
	v_cvt_pk_bf16_f32 v73, v74, v75
	v_cvt_pk_bf16_f32 v68, v68, v69
	v_cvt_pk_bf16_f32 v69, v70, v71
	v_cvt_pk_bf16_f32 v64, v64, v65
	v_cvt_pk_bf16_f32 v65, v66, v67
	s_waitcnt lgkmcnt(0)
	s_barrier
	ds_write_b64 v126, v[92:93]
	ds_write_b64 v122, v[88:89]
	ds_write_b64 v126, v[84:85] offset:4096
	ds_write_b64 v122, v[80:81] offset:4096
	ds_write_b64 v126, v[76:77] offset:8192
	ds_write_b64 v122, v[72:73] offset:8192
	ds_write_b64 v126, v[68:69] offset:12288
	ds_write_b64 v122, v[64:65] offset:12288
	s_waitcnt lgkmcnt(0)
	s_barrier
	ds_read_b128 v[64:67], v114
	ds_read_b128 v[68:71], v115
	ds_read_b128 v[72:75], v116
	ds_read_b128 v[76:79], v117
	s_waitcnt lgkmcnt(0)
	global_store_dwordx4 v[110:111], v[64:67], off offset:256 sc1
	global_store_dwordx4 v[112:113], v[68:71], off offset:256 sc1
	global_store_dwordx4 v[100:101], v[72:75], off offset:256 sc1
	global_store_dwordx4 v[96:97], v[76:79], off offset:256 sc1
	v_cvt_pk_bf16_f32 v60, v60, v61
	v_cvt_pk_bf16_f32 v61, v62, v63
	v_cvt_pk_bf16_f32 v56, v56, v57
	v_cvt_pk_bf16_f32 v57, v58, v59
	v_cvt_pk_bf16_f32 v52, v52, v53
	v_cvt_pk_bf16_f32 v53, v54, v55
	v_cvt_pk_bf16_f32 v48, v48, v49
	v_cvt_pk_bf16_f32 v49, v50, v51
	v_cvt_pk_bf16_f32 v44, v44, v45
	v_cvt_pk_bf16_f32 v45, v46, v47
	v_cvt_pk_bf16_f32 v40, v40, v41
	v_cvt_pk_bf16_f32 v41, v42, v43
	v_cvt_pk_bf16_f32 v36, v36, v37
	v_cvt_pk_bf16_f32 v37, v38, v39
	v_cvt_pk_bf16_f32 v32, v32, v33
	v_cvt_pk_bf16_f32 v33, v34, v35
	s_waitcnt lgkmcnt(0)
	s_barrier
	ds_write_b64 v126, v[60:61]
	ds_write_b64 v122, v[56:57]
	ds_write_b64 v126, v[52:53] offset:4096
	ds_write_b64 v122, v[48:49] offset:4096
	ds_write_b64 v126, v[44:45] offset:8192
	ds_write_b64 v122, v[40:41] offset:8192
	ds_write_b64 v126, v[36:37] offset:12288
	ds_write_b64 v122, v[32:33] offset:12288
	s_waitcnt lgkmcnt(0)
	s_barrier
	ds_read_b128 v[32:35], v114
	ds_read_b128 v[36:39], v115
	v_add_lshl_u32 v156, s15, v156, 10
	v_mov_b32_e32 v157, v133
	v_lshl_add_u64 v[46:47], v[156:157], 1, v[108:109]
	s_waitcnt lgkmcnt(0)
	global_store_dwordx4 v[46:47], v[32:35], off sc1
	ds_read_b128 v[32:35], v116
	ds_read_b128 v[40:43], v117
	v_mov_b32_e32 v159, v133
	v_add_lshl_u32 v160, s15, v160, 10
	v_mov_b32_e32 v161, v133
	v_lshl_add_u64 v[48:49], v[158:159], 1, v[108:109]
	v_add_lshl_u32 v44, s15, v170, 10
	v_mov_b32_e32 v45, v133
	global_store_dwordx4 v[48:49], v[36:39], off sc1
	v_cvt_pk_bf16_f32 v28, v28, v29
	v_cvt_pk_bf16_f32 v29, v30, v31
	v_lshl_add_u64 v[36:37], v[160:161], 1, v[108:109]
	s_waitcnt lgkmcnt(0)
	global_store_dwordx4 v[36:37], v[32:35], off sc1
	v_cvt_pk_bf16_f32 v24, v24, v25
	v_cvt_pk_bf16_f32 v25, v26, v27
	v_lshl_add_u64 v[32:33], v[44:45], 1, v[108:109]
	global_store_dwordx4 v[32:33], v[40:43], off sc1
	v_cvt_pk_bf16_f32 v20, v20, v21
	v_cvt_pk_bf16_f32 v21, v22, v23
	v_cvt_pk_bf16_f32 v16, v16, v17
	v_cvt_pk_bf16_f32 v17, v18, v19
	v_cvt_pk_bf16_f32 v12, v12, v13
	v_cvt_pk_bf16_f32 v13, v14, v15
	v_cvt_pk_bf16_f32 v8, v8, v9
	v_cvt_pk_bf16_f32 v9, v10, v11
	v_cvt_pk_bf16_f32 v4, v4, v5
	v_cvt_pk_bf16_f32 v5, v6, v7
	v_cvt_pk_bf16_f32 v0, v0, v1
	v_cvt_pk_bf16_f32 v1, v2, v3
	s_waitcnt lgkmcnt(0)
	s_barrier
	ds_write_b64 v126, v[28:29]
	ds_write_b64 v122, v[24:25]
	ds_write_b64 v126, v[20:21] offset:4096
	ds_write_b64 v122, v[16:17] offset:4096
	ds_write_b64 v126, v[12:13] offset:8192
	ds_write_b64 v122, v[8:9] offset:8192
	ds_write_b64 v126, v[4:5] offset:12288
	ds_write_b64 v122, v[0:1] offset:12288
	s_waitcnt lgkmcnt(0)
	s_barrier
	ds_read_b128 v[0:3], v114
	ds_read_b128 v[4:7], v115
	ds_read_b128 v[8:11], v116
	ds_read_b128 v[12:15], v117
	s_waitcnt lgkmcnt(0)
	global_store_dwordx4 v[46:47], v[0:3], off offset:256 sc1
	global_store_dwordx4 v[48:49], v[4:7], off offset:256 sc1
	global_store_dwordx4 v[36:37], v[8:11], off offset:256 sc1
	global_store_dwordx4 v[32:33], v[12:15], off offset:256 sc1
	s_waitcnt lgkmcnt(0)
	s_barrier
	s_and_b64 vcc, exec, s[0:1]
	s_mov_b32 s45, s14
	s_mov_b32 s4, s8
	s_mov_b64 s[22:23], s[18:19]
	s_mov_b64 s[20:21], s[16:17]
	s_cbranch_vccz .LBB0_980
	v_readlane_b32 s0, v252, 59
	s_waitcnt vmcnt(0)
	v_readlane_b32 s1, v252, 60
	s_andn2_b64 vcc, exec, s[0:1]
	s_cbranch_vccnz .LBB0_987
	s_barrier
